# static priority raise for waves 4-7 now set before the retention unit (covers retention + attention, reset after attention)
# baseline (speedup 1.0000x reference)
; #define LAS __attribute__((address_space(3)))
; DI u32x4 pack8(const float* f) { u32x4 o; o.x = pk2(f[0], f[1]); o.y = pk2(f[2], f[3]); o.z = pk2(f[4], f[5]); o.w = pk2(f[6], f[7]); return o; }
; DI void ret_phase(const KArgs& a, int zz, int e, const bf16_t* Z, bf16_t* OF, bf16_t* OB, LAS unsigned char* lds, int G, int bid, int tid, int wave, int lane) {
;     const f32x2* tabr = (const f32x2*)(a.ws + zz + OFF_TABR);
;     const int fr = lane & 15, fq = lane >> 4;
;     LAS bf16_t* Qs = (LAS bf16_t*)(lds + RT_Q); LAS bf16_t* Ks = (LAS bf16_t*)(lds + RT_K); LAS bf16_t* KTs = (LAS bf16_t*)(lds + RT_KT);
;     LAS bf16_t* VTs = (LAS bf16_t*)(lds + RT_VT); LAS bf16_t* STs = (LAS bf16_t*)(lds + RT_ST);
;     for (int u = bid; u < NB * 8 * 2; u += G) {
;         const int dir = u & 1, h = (u >> 1) & 7, b = u >> 4;
;         bf16_t* O = dir ? OB : OF;
;         const float raw = a.in[zz + (dir ? 18 : 17)][e * 8 + h];
;         const float lg2 = log1pf(-exp2f(raw)) * LOG2E;
;         const float cd = exp2f(128.f * lg2);
;         for (int i = tid; i < 64 * 72 / 2; i += NTHREADS) ((LAS unsigned*)STs)[i] = 0u;
;         f32x4 sacc[2]; sacc[0] = (f32x4){0.f, 0.f, 0.f, 0.f}; sacc[1] = (f32x4){0.f, 0.f, 0.f, 0.f};
;         const int et_s = wave >> 1, dt0 = (wave & 1) * 2;
;         __syncthreads();
;         u32x4 fq1_, fq2_, fk1_, fk2_, fv1_, fv2_;
;         auto chunk_row0 = [&](const int ci, int& t0o, bool& sego) __attribute__((always_inline)) -> size_t {
;     ...
;                     for (int q = 0; q < 8; ++q) { const int jt = 2 * kk + (q >> 2), jj = q & 3; const int j = 16 * jt + fq * 4 + jj;
;                         const int diff = dir ? j - il : il - j; const bool valid = dir ? diff > 0 : diff >= 0;
;                         p[q] = valid ? st[jt][jj] * __builtin_amdgcn_exp2f((float)diff * lg2) : 0.f; }
;                     Pf[kk] = __builtin_bit_cast(bf16x8, pack8(p)); }
;                 const float qd = __builtin_amdgcn_exp2f((float)(dir ? 128 - il : il + 1) * lg2);
.LBB0_432:
	s_andn2_b64 vcc, exec, s[0:1]
	s_cbranch_vccnz .LBB0_462
	v_writelane_b32 v255, s37, 5
	v_writelane_b32 v255, s36, 6
	s_cmpk_gt_i32 s96, 0xff
	s_nop 0
	v_writelane_b32 v255, s37, 7
	s_cbranch_scc1 .LBB0_441
	s_add_i32 s0, s78, 17
	v_writelane_b32 v253, s0, 17
	v_readlane_b32 s7, v255, 5
	v_readlane_b32 s0, v253, 9
	v_readlane_b32 s1, v253, 10
	s_and_b64 s[0:1], s[0:1], exec
	s_cselect_b32 s0, 8, 0
	v_writelane_b32 v253, s0, 36
	s_movk_i32 s0, 0x900
	v_cmp_gt_i32_e64 s[0:1], s0, v153
	v_and_b32_e32 v6, 3, v153
	v_lshlrev_b32_e32 v148, 6, v6
	v_writelane_b32 v253, s0, 38
	v_and_b32_e32 v1, 15, v153
	v_ashrrev_i32_e32 v64, 2, v153
	v_writelane_b32 v253, s1, 39
	s_lshl_b32 s0, s7, 1
	s_and_b32 s4, s0, 2
	v_lshl_add_u64 v[4:5], s[84:85], 0, v[148:149]
	s_mov_b64 s[0:1], 0x6958000
	s_movk_i32 s5, 0x90
	v_lshlrev_b32_e32 v2, 4, v6
	v_lshl_add_u64 v[66:67], v[4:5], 0, s[0:1]
	v_mul_lo_u32 v4, v64, s5
	v_lshl_or_b32 v68, s7, 4, v1
	v_lshrrev_b32_e32 v3, 4, v152
	v_add3_u32 v90, 0, v4, v2
	v_mul_lo_u32 v4, v68, s5
	v_lshlrev_b32_e32 v0, 3, v6
	v_add_u32_e32 v5, 0, v4
	v_lshlrev_b32_e32 v4, 2, v3
	v_mul_u32_u24_e32 v11, 0x880, v6
	v_lshlrev_b32_e32 v12, 1, v64
	v_mul_u32_u24_e32 v6, 0x1100, v6
	v_add3_u32 v97, 0, v11, v12
	v_add3_u32 v98, 0, v6, v12
	v_or_b32_e32 v12, 1, v4
	v_sub_u32_e32 v103, v12, v68
	v_sub_u32_e32 v104, v68, v12
	v_or_b32_e32 v12, 2, v4
	v_sub_u32_e32 v105, v12, v68
	v_sub_u32_e32 v106, v68, v12
	v_or_b32_e32 v12, 3, v4
	v_sub_u32_e32 v107, v12, v68
	v_sub_u32_e32 v108, v68, v12
	v_or_b32_e32 v12, 16, v4
	v_sub_u32_e32 v109, v12, v68
	v_sub_u32_e32 v110, v68, v12
	v_or_b32_e32 v12, 17, v4
	v_sub_u32_e32 v111, v12, v68
	v_sub_u32_e32 v112, v68, v12
	v_or_b32_e32 v12, 18, v4
	v_sub_u32_e32 v113, v12, v68
	v_sub_u32_e32 v114, v68, v12
	v_or_b32_e32 v12, 19, v4
	v_sub_u32_e32 v115, v12, v68
	v_sub_u32_e32 v116, v68, v12
	v_or_b32_e32 v12, 32, v4
	v_sub_u32_e32 v117, v12, v68
	v_sub_u32_e32 v118, v68, v12
	v_or_b32_e32 v12, 33, v4
	v_sub_u32_e32 v119, v12, v68
	v_sub_u32_e32 v120, v68, v12
	v_or_b32_e32 v12, 34, v4
	v_sub_u32_e32 v121, v12, v68
	v_sub_u32_e32 v122, v68, v12
	v_or_b32_e32 v12, 35, v4
	v_sub_u32_e32 v123, v12, v68
	v_sub_u32_e32 v124, v68, v12
	v_or_b32_e32 v12, 48, v4
	v_sub_u32_e32 v125, v12, v68
	v_sub_u32_e32 v126, v68, v12
	v_or_b32_e32 v12, 49, v4
	v_sub_u32_e32 v127, v12, v68
	v_sub_u32_e32 v128, v68, v12
	v_or_b32_e32 v12, 50, v4
	v_sub_u32_e32 v129, v12, v68
	v_sub_u32_e32 v130, v68, v12
	v_or_b32_e32 v12, 51, v4
	v_sub_u32_e32 v131, v12, v68
	v_sub_u32_e32 v132, v68, v12
	v_or_b32_e32 v12, 64, v4
	v_sub_u32_e32 v133, v12, v68
	v_sub_u32_e32 v134, v68, v12
	v_or_b32_e32 v12, 0x41, v4
	v_sub_u32_e32 v135, v12, v68
	v_sub_u32_e32 v136, v68, v12
	v_or_b32_e32 v12, 0x42, v4
	v_sub_u32_e32 v137, v12, v68
	v_sub_u32_e32 v138, v68, v12
	v_or_b32_e32 v12, 0x43, v4
	v_sub_u32_e32 v139, v12, v68
	v_sub_u32_e32 v140, v68, v12
	v_or_b32_e32 v12, 0x50, v4
	v_sub_u32_e32 v141, v12, v68
	v_sub_u32_e32 v142, v68, v12
	v_or_b32_e32 v12, 0x51, v4
	v_sub_u32_e32 v143, v12, v68
	v_sub_u32_e32 v155, v68, v12
	v_or_b32_e32 v12, 0x52, v4
	v_sub_u32_e32 v156, v12, v68
	v_sub_u32_e32 v157, v68, v12
	v_or_b32_e32 v12, 0x53, v4
	v_sub_u32_e32 v158, v12, v68
	v_sub_u32_e32 v159, v68, v12
	v_or_b32_e32 v12, 0x60, v4
	v_sub_u32_e32 v160, v12, v68
	v_sub_u32_e32 v161, v68, v12
	v_or_b32_e32 v12, 0x61, v4
	v_sub_u32_e32 v162, v12, v68
	v_sub_u32_e32 v163, v68, v12
	v_or_b32_e32 v12, 0x62, v4
	v_sub_u32_e32 v164, v12, v68
	v_sub_u32_e32 v165, v68, v12
	v_or_b32_e32 v12, 0x63, v4
	s_lshl_b32 s0, s7, 3
	v_sub_u32_e32 v166, v12, v68
	v_sub_u32_e32 v167, v68, v12
	v_or_b32_e32 v12, 0x70, v4
	v_bfi_b32 v9, -16, s0, v153
	s_movk_i32 s1, 0x110
	v_sub_u32_e32 v168, v12, v68
	v_sub_u32_e32 v169, v68, v12
	v_or_b32_e32 v12, 0x71, v4
	v_writelane_b32 v253, s78, 34
	v_mul_lo_u32 v9, v9, s1
	v_and_b32_e32 v10, 48, v152
	v_sub_u32_e32 v170, v12, v68
	v_sub_u32_e32 v171, v68, v12
	v_or_b32_e32 v12, 0x72, v4
	v_writelane_b32 v253, s79, 35
	v_lshlrev_b32_e32 v3, 3, v3
	v_readlane_b32 s6, v254, 30
	v_add3_u32 v96, 0, v9, v10
	v_and_or_b32 v9, s0, -16, v4
	v_sub_u32_e32 v172, v12, v68
	v_sub_u32_e32 v173, v68, v12
	v_or_b32_e32 v12, 0x73, v4
	s_or_b32 s0, s4, 1
	v_writelane_b32 v253, s86, 13
	v_and_b32_e32 v7, 48, v153
	v_add_u32_e32 v8, 0, v3
	v_lshl_add_u32 v10, v1, 1, s6
	v_mul_u32_u24_e32 v99, 0x90, v1
	v_or_b32_e32 v6, 48, v152
	v_or_b32_e32 v11, 0x70, v152
	v_sub_u32_e32 v174, v12, v68
	v_sub_u32_e32 v175, v68, v12
	v_mul_u32_u24_e32 v12, 0x110, v1
	v_lshl_or_b32 v13, s4, 4, v1
	v_lshl_or_b32 v1, s0, 4, v1
	v_writelane_b32 v253, s87, 14
	v_add_u32_e32 v92, 0, v7
	v_add_u32_e32 v3, v8, v3
	v_mul_u32_u24_e32 v100, 0x90, v6
	v_mul_u32_u24_e32 v11, 0x90, v11
	v_mul_u32_u24_e32 v6, 0x110, v6
	v_mul_u32_u24_e32 v13, 0x110, v13
	v_mul_u32_u24_e32 v1, 0x110, v1
	v_lshl_add_u32 v14, s4, 5, v10
	v_mul_lo_u32 v9, v9, s5
	v_lshl_add_u32 v10, s0, 5, v10
	v_writelane_b32 v253, s48, 15
	v_ashrrev_i32_e32 v65, 31, v64
	v_sub_u32_e32 v91, 0x7f, v64
	v_sub_u32_e32 v93, 0x80, v68
	v_add_u32_e32 v94, 1, v68
	v_add_u32_e32 v95, s6, v7
	v_ashrrev_i32_e32 v69, 31, v68
	v_sub_u32_e32 v101, v4, v68
	v_sub_u32_e32 v102, v68, v4
	v_add_u32_e32 v176, 0xfffffe00, v153
	v_lshl_add_u32 v177, v153, 2, s6
	v_lshlrev_b32_e32 v148, 1, v0
	v_lshlrev_b32_e32 v70, 1, v2
	v_lshlrev_b32_e32 v72, 1, v4
	v_add_u32_e32 v178, v5, v7
	v_add_u32_e32 v179, v92, v11
	v_add_u32_e32 v180, v8, v12
	v_add_u32_e32 v181, v8, v6
	v_add_u32_e32 v182, v3, v13
	v_add_u32_e32 v183, v3, v1
	v_add_u32_e32 v184, v14, v9
	v_add_u32_e32 v185, v10, v9
	s_mov_b32 s23, s96
	v_writelane_b32 v253, s49, 16
	v_writelane_b32 v255, s69, 8
	v_readfirstlane_b32 s98, v153
	s_nop 3
	s_lshr_b32 s98, s98, 6
	s_cmp_ge_u32 s98, 4
	s_cbranch_scc0 .Lattn_prio_done
	s_setprio 1
.Lattn_prio_done:
.LBB0_435:
	s_and_b32 s7, s23, 1
	v_readlane_b32 s0, v253, 17
	s_add_i32 s0, s0, s7
	s_ashr_i32 s1, s0, 31
	s_bfe_u32 s6, s23, 0x30001
	s_lshl_b64 s[0:1], s[0:1], 3
	v_readlane_b32 s4, v253, 5
	v_readlane_b32 s5, v253, 6
	s_add_u32 s0, s4, s0
	s_addc_u32 s1, s5, s1
	s_load_dwordx2 s[0:1], s[0:1], 0x0
	v_readlane_b32 s4, v253, 36
	s_or_b32 s4, s6, s4
	s_lshl_b32 s4, s4, 2
	s_waitcnt vmcnt(5)
	v_mov_b32_e32 v0, s4
	s_waitcnt lgkmcnt(0)
	global_load_dword v0, v0, s[0:1]
	s_mov_b64 s[0:1], exec
	v_readlane_b32 s4, v253, 38
	v_readlane_b32 s5, v253, 39
	s_and_b64 s[4:5], s[0:1], s[4:5]
	s_mov_b32 s22, 0x3e000000
	s_mov_b64 exec, s[4:5]
	s_cbranch_execz .LBB0_438
	s_mov_b64 s[4:5], 0
	v_mov_b32_e32 v1, v177
	v_mov_b32_e32 v2, v176
